# P4 fix-up inner loop hand-rewritten: next row's loads issued before computing the current row (double-buffered, vmcnt(4)), channel-pair packed FMA/mul
# speedup vs baseline: 1.0104x; 1.0023x over previous
; DI void phase_fixup(const Params& p) {
;     ...
;     for (int it = blockIdx.x; it < 512; it += gridDim.x) {
;         const int c = it >> 2, rq = it & 3;
;         float cf[8], cb[8];
;         { const f32x4 a0 = *(const f32x4*)(CAR + (size_t)c * 2048 + ch), a1 = *(const f32x4*)(CAR + (size_t)c * 2048 + ch + 4);
;           const f32x4 b0 = *(const f32x4*)(CAR + (size_t)(128 + c) * 2048 + ch), b1 = *(const f32x4*)(CAR + (size_t)(128 + c) * 2048 + ch + 4);
; #pragma unroll
;           for (int i = 0; i < 4; ++i) { cf[i] = a0[i] * (1.f / 255.f); cf[4 + i] = a1[i] * (1.f / 255.f); cb[i] = b0[i] * (1.f / 255.f); cb[4 + i] = b1[i] * (1.f / 255.f); } }
; #pragma unroll 8
;         for (int i = 0; i < 16; ++i) {
;             const size_t off = (size_t)(c * 128 + rq * 32 + 2 * i + r2) * 2048 + ch;
;             const u32x4 g = __builtin_nontemporal_load((const u32x4*)(ZG + off)), h = __builtin_nontemporal_load((const u32x4*)(HLp + off)), pp = __builtin_nontemporal_load((const u32x4*)(PPp + off));
.LBB0_377:
	s_ashr_i32 s20, s17, 2
	s_ashr_i32 s21, s20, 31
	s_lshl_b64 s[18:19], s[20:21], 13
	v_lshl_add_u64 v[2:3], v[0:1], 0, s[18:19]
	v_add_co_u32_e32 v12, vcc, 0x100000, v2
	global_load_dwordx4 v[14:17], v[2:3], off offset:16
	global_load_dwordx4 v[18:21], v[2:3], off
	v_addc_co_u32_e32 v13, vcc, 0, v3, vcc
	v_lshl_add_u64 v[10:11], v[2:3], 0, s[6:7]
	global_load_dwordx4 v[2:5], v[12:13], off
	global_load_dwordx4 v[6:9], v[10:11], off offset:16
	s_and_b32 s19, s15, 0x60
	v_lshl_or_b32 v26, s20, 7, v50
	s_mov_b32 s18, 0
	v_or_b32_e32 v52, s19, v26
	v_lshl_or_b32 v22, v52, 12, v51
	v_mov_b32_e32 v70, v22
	s_mov_b32 s40, 0xbfb8aa3b
	global_load_dwordx4 v[28:31], v70, s[10:11] nt
	global_load_dwordx4 v[32:35], v70, s[4:5] nt
	global_load_dwordx4 v[36:39], v70, s[12:13] nt
	s_waitcnt vmcnt(3)
	v_pk_mul_f32 v[18:19], v[18:19], s[14:15] op_sel_hi:[1,0]
	v_pk_mul_f32 v[20:21], v[20:21], s[14:15] op_sel_hi:[1,0]
	v_pk_mul_f32 v[14:15], v[14:15], s[14:15] op_sel_hi:[1,0]
	v_pk_mul_f32 v[16:17], v[16:17], s[14:15] op_sel_hi:[1,0]
	v_pk_mul_f32 v[2:3], v[2:3], s[14:15] op_sel_hi:[1,0]
	v_pk_mul_f32 v[4:5], v[4:5], s[14:15] op_sel_hi:[1,0]
	v_pk_mul_f32 v[6:7], v[6:7], s[14:15] op_sel_hi:[1,0]
	v_pk_mul_f32 v[8:9], v[8:9], s[14:15] op_sel_hi:[1,0]
	s_waitcnt vmcnt(0)
; DI unsigned cvtpk(float lo, float hi) { unsigned r; asm volatile("v_cvt_pk_bf16_f32 %0, %1, %2" : "=v"(r) : "v"(lo), "v"(hi)); return r; }
; DI float bflo(unsigned w) { return __uint_as_float(w << 16); }
; DI float bfhi(unsigned w) { return __uint_as_float(w & 0xffff0000u); }
; DI float sigm(float x) { return rcpf_(1.f + ex2(-x * LOG2E)); }
; DI float ub(unsigned w, int i) { return (float)((w >> (8 * i)) & 0xffu); }
; DI void phase_fixup(const Params& p) {
;     ...
;         for (int i = 0; i < 16; ++i) {
;             const size_t off = (size_t)(c * 128 + rq * 32 + 2 * i + r2) * 2048 + ch;
;             const u32x4 g = __builtin_nontemporal_load((const u32x4*)(ZG + off)), h = __builtin_nontemporal_load((const u32x4*)(HLp + off)), pp = __builtin_nontemporal_load((const u32x4*)(PPp + off));
;             u32x4 o;
; #pragma unroll
;             for (int k = 0; k < 4; ++k) {
;                 const float g0 = bflo(g[k]), g1 = bfhi(g[k]);
;                 const float y0 = (bflo(h[k]) + ub(pp[k], 0) * cf[2 * k] + ub(pp[k], 1) * cb[2 * k]) * g0 * sigm(g0);
;                 const float y1 = (bfhi(h[k]) + ub(pp[k], 2) * cf[2 * k + 1] + ub(pp[k], 3) * cb[2 * k + 1]) * g1 * sigm(g1);
;                 o[k] = cvtpk(y0, y1);
;             }
;             *(u32x4*)(ZG + off) = o;
;         }
.Lp4_row_loop:
	s_add_i32 s42, s18, 1
	s_min_u32 s42, s42, 15
	s_lshl_b32 s42, s42, 13
	v_add_u32_e32 v71, s42, v22
	global_load_dwordx4 v[54:57], v71, s[10:11] nt
	global_load_dwordx4 v[58:61], v71, s[4:5] nt
	global_load_dwordx4 v[62:65], v71, s[12:13] nt
	s_waitcnt vmcnt(4)
	v_lshlrev_b32_e32 v72, 16, v28
	v_and_b32_e32 v73, 0xffff0000, v28
	v_lshlrev_b32_e32 v80, 16, v32
	v_and_b32_e32 v81, 0xffff0000, v32
	v_cvt_f32_ubyte0_e32 v88, v36
	v_cvt_f32_ubyte2_e32 v89, v36
	v_cvt_f32_ubyte1_e32 v96, v36
	v_cvt_f32_ubyte3_e32 v97, v36
	v_lshlrev_b32_e32 v74, 16, v29
	v_and_b32_e32 v75, 0xffff0000, v29
	v_lshlrev_b32_e32 v82, 16, v33
	v_and_b32_e32 v83, 0xffff0000, v33
	v_cvt_f32_ubyte0_e32 v90, v37
	v_cvt_f32_ubyte2_e32 v91, v37
	v_cvt_f32_ubyte1_e32 v98, v37
	v_cvt_f32_ubyte3_e32 v99, v37
	v_lshlrev_b32_e32 v76, 16, v30
	v_and_b32_e32 v77, 0xffff0000, v30
	v_lshlrev_b32_e32 v84, 16, v34
	v_and_b32_e32 v85, 0xffff0000, v34
	v_cvt_f32_ubyte0_e32 v92, v38
	v_cvt_f32_ubyte2_e32 v93, v38
	v_cvt_f32_ubyte1_e32 v100, v38
	v_cvt_f32_ubyte3_e32 v101, v38
	v_lshlrev_b32_e32 v78, 16, v31
	v_and_b32_e32 v79, 0xffff0000, v31
	v_lshlrev_b32_e32 v86, 16, v35
	v_and_b32_e32 v87, 0xffff0000, v35
	v_cvt_f32_ubyte0_e32 v94, v39
	v_cvt_f32_ubyte2_e32 v95, v39
	v_cvt_f32_ubyte1_e32 v102, v39
	v_cvt_f32_ubyte3_e32 v103, v39
	v_pk_mul_f32 v[104:105], v[72:73], s[40:41] op_sel_hi:[1,0]
	v_pk_mul_f32 v[106:107], v[74:75], s[40:41] op_sel_hi:[1,0]
	v_pk_mul_f32 v[108:109], v[76:77], s[40:41] op_sel_hi:[1,0]
	v_pk_mul_f32 v[110:111], v[78:79], s[40:41] op_sel_hi:[1,0]
	v_pk_fma_f32 v[80:81], v[88:89], v[18:19], v[80:81]
	v_pk_fma_f32 v[82:83], v[90:91], v[20:21], v[82:83]
	v_pk_fma_f32 v[84:85], v[92:93], v[14:15], v[84:85]
	v_pk_fma_f32 v[86:87], v[94:95], v[16:17], v[86:87]
	v_exp_f32_e32 v104, v104
	v_exp_f32_e32 v105, v105
	v_exp_f32_e32 v106, v106
	v_exp_f32_e32 v107, v107
	v_exp_f32_e32 v108, v108
	v_exp_f32_e32 v109, v109
	v_exp_f32_e32 v110, v110
	v_exp_f32_e32 v111, v111
	v_pk_fma_f32 v[80:81], v[96:97], v[2:3], v[80:81]
	v_pk_fma_f32 v[82:83], v[98:99], v[4:5], v[82:83]
	v_pk_fma_f32 v[84:85], v[100:101], v[6:7], v[84:85]
	v_pk_fma_f32 v[86:87], v[102:103], v[8:9], v[86:87]
	v_pk_add_f32 v[104:105], v[104:105], 1.0 op_sel_hi:[1,0]
	v_pk_add_f32 v[106:107], v[106:107], 1.0 op_sel_hi:[1,0]
	v_pk_add_f32 v[108:109], v[108:109], 1.0 op_sel_hi:[1,0]
	v_pk_add_f32 v[110:111], v[110:111], 1.0 op_sel_hi:[1,0]
	v_rcp_f32_e32 v104, v104
	v_rcp_f32_e32 v105, v105
	v_rcp_f32_e32 v106, v106
	v_rcp_f32_e32 v107, v107
	v_rcp_f32_e32 v108, v108
	v_rcp_f32_e32 v109, v109
	v_rcp_f32_e32 v110, v110
	v_rcp_f32_e32 v111, v111
	v_pk_mul_f32 v[80:81], v[80:81], v[72:73]
	v_pk_mul_f32 v[82:83], v[82:83], v[74:75]
	v_pk_mul_f32 v[84:85], v[84:85], v[76:77]
	v_pk_mul_f32 v[86:87], v[86:87], v[78:79]
	v_pk_mul_f32 v[80:81], v[104:105], v[80:81]
	v_pk_mul_f32 v[82:83], v[106:107], v[82:83]
	v_pk_mul_f32 v[84:85], v[108:109], v[84:85]
	v_pk_mul_f32 v[86:87], v[110:111], v[86:87]
	v_cvt_pk_bf16_f32 v24, v80, v81
	v_cvt_pk_bf16_f32 v25, v82, v83
	v_cvt_pk_bf16_f32 v26, v84, v85
	v_cvt_pk_bf16_f32 v27, v86, v87
	global_store_dwordx4 v70, v[24:27], s[10:11]
	s_add_i32 s42, s18, 2
	s_min_u32 s42, s42, 15
	s_lshl_b32 s42, s42, 13
	v_add_u32_e32 v70, s42, v22
	global_load_dwordx4 v[28:31], v70, s[10:11] nt
	global_load_dwordx4 v[32:35], v70, s[4:5] nt
	global_load_dwordx4 v[36:39], v70, s[12:13] nt
	s_waitcnt vmcnt(4)
	v_lshlrev_b32_e32 v72, 16, v54
	v_and_b32_e32 v73, 0xffff0000, v54
	v_lshlrev_b32_e32 v80, 16, v58
	v_and_b32_e32 v81, 0xffff0000, v58
	v_cvt_f32_ubyte0_e32 v88, v62
	v_cvt_f32_ubyte2_e32 v89, v62
	v_cvt_f32_ubyte1_e32 v96, v62
	v_cvt_f32_ubyte3_e32 v97, v62
	v_lshlrev_b32_e32 v74, 16, v55
	v_and_b32_e32 v75, 0xffff0000, v55
	v_lshlrev_b32_e32 v82, 16, v59
	v_and_b32_e32 v83, 0xffff0000, v59
	v_cvt_f32_ubyte0_e32 v90, v63
	v_cvt_f32_ubyte2_e32 v91, v63
	v_cvt_f32_ubyte1_e32 v98, v63
	v_cvt_f32_ubyte3_e32 v99, v63
	v_lshlrev_b32_e32 v76, 16, v56
	v_and_b32_e32 v77, 0xffff0000, v56
	v_lshlrev_b32_e32 v84, 16, v60
	v_and_b32_e32 v85, 0xffff0000, v60
	v_cvt_f32_ubyte0_e32 v92, v64
	v_cvt_f32_ubyte2_e32 v93, v64
	v_cvt_f32_ubyte1_e32 v100, v64
	v_cvt_f32_ubyte3_e32 v101, v64
	v_lshlrev_b32_e32 v78, 16, v57
	v_and_b32_e32 v79, 0xffff0000, v57
	v_lshlrev_b32_e32 v86, 16, v61
	v_and_b32_e32 v87, 0xffff0000, v61
	v_cvt_f32_ubyte0_e32 v94, v65
	v_cvt_f32_ubyte2_e32 v95, v65
	v_cvt_f32_ubyte1_e32 v102, v65
	v_cvt_f32_ubyte3_e32 v103, v65
	v_pk_mul_f32 v[104:105], v[72:73], s[40:41] op_sel_hi:[1,0]
	v_pk_mul_f32 v[106:107], v[74:75], s[40:41] op_sel_hi:[1,0]
	v_pk_mul_f32 v[108:109], v[76:77], s[40:41] op_sel_hi:[1,0]
	v_pk_mul_f32 v[110:111], v[78:79], s[40:41] op_sel_hi:[1,0]
	v_pk_fma_f32 v[80:81], v[88:89], v[18:19], v[80:81]
	v_pk_fma_f32 v[82:83], v[90:91], v[20:21], v[82:83]
	v_pk_fma_f32 v[84:85], v[92:93], v[14:15], v[84:85]
	v_pk_fma_f32 v[86:87], v[94:95], v[16:17], v[86:87]
	v_exp_f32_e32 v104, v104
	v_exp_f32_e32 v105, v105
	v_exp_f32_e32 v106, v106
	v_exp_f32_e32 v107, v107
	v_exp_f32_e32 v108, v108
	v_exp_f32_e32 v109, v109
	v_exp_f32_e32 v110, v110
	v_exp_f32_e32 v111, v111
	v_pk_fma_f32 v[80:81], v[96:97], v[2:3], v[80:81]
	v_pk_fma_f32 v[82:83], v[98:99], v[4:5], v[82:83]
	v_pk_fma_f32 v[84:85], v[100:101], v[6:7], v[84:85]
	v_pk_fma_f32 v[86:87], v[102:103], v[8:9], v[86:87]
	v_pk_add_f32 v[104:105], v[104:105], 1.0 op_sel_hi:[1,0]
	v_pk_add_f32 v[106:107], v[106:107], 1.0 op_sel_hi:[1,0]
	v_pk_add_f32 v[108:109], v[108:109], 1.0 op_sel_hi:[1,0]
	v_pk_add_f32 v[110:111], v[110:111], 1.0 op_sel_hi:[1,0]
	v_rcp_f32_e32 v104, v104
	v_rcp_f32_e32 v105, v105
	v_rcp_f32_e32 v106, v106
	v_rcp_f32_e32 v107, v107
	v_rcp_f32_e32 v108, v108
	v_rcp_f32_e32 v109, v109
	v_rcp_f32_e32 v110, v110
	v_rcp_f32_e32 v111, v111
	v_pk_mul_f32 v[80:81], v[80:81], v[72:73]
	v_pk_mul_f32 v[82:83], v[82:83], v[74:75]
	v_pk_mul_f32 v[84:85], v[84:85], v[76:77]
	v_pk_mul_f32 v[86:87], v[86:87], v[78:79]
	v_pk_mul_f32 v[80:81], v[104:105], v[80:81]
	v_pk_mul_f32 v[82:83], v[106:107], v[82:83]
	v_pk_mul_f32 v[84:85], v[108:109], v[84:85]
	v_pk_mul_f32 v[86:87], v[110:111], v[86:87]
	v_cvt_pk_bf16_f32 v66, v80, v81
	v_cvt_pk_bf16_f32 v67, v82, v83
	v_cvt_pk_bf16_f32 v68, v84, v85
	v_cvt_pk_bf16_f32 v69, v86, v87
	global_store_dwordx4 v71, v[66:69], s[10:11]
	s_add_i32 s18, s18, 2
	s_cmp_lt_u32 s18, 16
	s_cbranch_scc1 .Lp4_row_loop
	s_add_i32 s17, s17, s24
	s_add_i32 s15, s15, s16
	s_cmpk_gt_i32 s17, 0x1ff
	s_cbranch_scc0 .LBB0_377
	s_load_dwordx2 s[4:5], s[0:1], 0xc8
	s_waitcnt lgkmcnt(0)
	v_mov_b64_e32 v[0:1], s[4:5]
